# P3 step e: -w tile stored as 8 dword stores per lane (row pairs via cvt_pk + DPP + v_perm) instead of 16 two-byte stores (store widening)
# baseline (speedup 1.0000x reference)
.LBB0_295:
	s_nop 7
	v_or_b32_e32 v0, s25, v42
	v_lshlrev_b32_e32 v2, 4, v37
	v_mul_u32_u24_e32 v1, 0x90, v0
	v_bitop3_b32 v3, v2, v36, 16 bitop3:0x78
	v_add3_u32 v19, s24, v1, v3
	s_add_i32 s35, 0, 0x1a400
	s_waitcnt lgkmcnt(0)
	s_barrier
	v_add_u32_e32 v1, s35, v2
	s_movk_i32 s35, 0x70
	v_add_u32_e32 v21, s25, v19
	v_and_or_b32 v18, v0, s35, v43
	v_add_u32_e32 v20, v1, v46
	ds_read_b128 v[0:3], v21
	ds_read_b128 v[4:7], v20
	ds_read_b128 v[24:27], v20 offset:32
	s_waitcnt lgkmcnt(1)
	v_mfma_f32_32x32x16_bf16 v[0:15], v[4:7], v[0:3], 0
	v_add_u32_e32 v22, s97, v19
	ds_read_b128 v[28:31], v22
	s_ashr_i32 s9, s8, 31
	s_lshl_b64 s[54:55], s[8:9], 3
	s_add_u32 s54, s54, s26
	s_addc_u32 s55, s55, 0
	s_mov_b64 s[56:57], -1
	s_waitcnt lgkmcnt(0)
	v_mfma_f32_32x32x16_bf16 v[0:15], v[24:27], v[28:31], v[0:15]
	s_and_b64 vcc, exec, s[66:67]
	v_mul_u32_u24_e32 v23, 0x220, v37
	s_cbranch_vccz .LBB0_297
	s_nop 8
	v_add_lshl_u32 v196, v18, v23, 1
	v_and_b32_e32 v17, 1, v211
	v_cmp_eq_u32_e32 vcc, 0, v17
	v_mov_b32_e32 v16, 0x3020706
	v_mov_b32_e32 v31, 0x5040100
	v_cndmask_b32_e32 v16, v16, v31, vcc
	v_mul_u32_u24_e32 v17, 0x10e, v17
	v_add_u32_e32 v196, v196, v17
	v_add_u32_e32 v17, 0x1000, v196
	v_cvt_pk_bf16_f32 v24, -v0, -v1
	v_cvt_pk_bf16_f32 v25, -v2, -v3
	v_cvt_pk_bf16_f32 v26, -v4, -v5
	v_cvt_pk_bf16_f32 v27, -v6, -v7
	v_mov_b32_dpp v28, v24 quad_perm:[1,0,3,2] row_mask:0xf bank_mask:0xf
	v_mov_b32_dpp v29, v25 quad_perm:[1,0,3,2] row_mask:0xf bank_mask:0xf
	v_mov_b32_dpp v30, v26 quad_perm:[1,0,3,2] row_mask:0xf bank_mask:0xf
	v_mov_b32_dpp v31, v27 quad_perm:[1,0,3,2] row_mask:0xf bank_mask:0xf
	v_perm_b32 v24, v28, v24, v16
	v_perm_b32 v25, v29, v25, v16
	v_perm_b32 v26, v30, v26, v16
	v_perm_b32 v27, v31, v27, v16
	global_store_dword v196, v24, s[76:77]
	global_store_dword v196, v25, s[76:77] offset:544
	global_store_dword v196, v26, s[76:77] offset:2176
	global_store_dword v196, v27, s[76:77] offset:2720
	v_cvt_pk_bf16_f32 v24, -v8, -v9
	v_cvt_pk_bf16_f32 v25, -v10, -v11
	v_cvt_pk_bf16_f32 v26, -v12, -v13
	v_cvt_pk_bf16_f32 v27, -v14, -v15
	v_mov_b32_dpp v28, v24 quad_perm:[1,0,3,2] row_mask:0xf bank_mask:0xf
	v_mov_b32_dpp v29, v25 quad_perm:[1,0,3,2] row_mask:0xf bank_mask:0xf
	v_mov_b32_dpp v30, v26 quad_perm:[1,0,3,2] row_mask:0xf bank_mask:0xf
	v_mov_b32_dpp v31, v27 quad_perm:[1,0,3,2] row_mask:0xf bank_mask:0xf
	v_perm_b32 v24, v28, v24, v16
	v_perm_b32 v25, v29, v25, v16
	v_perm_b32 v26, v30, v26, v16
	v_perm_b32 v27, v31, v27, v16
	global_store_dword v17, v24, s[76:77] offset:256
	global_store_dword v17, v25, s[76:77] offset:800
	global_store_dword v17, v26, s[76:77] offset:2432
	global_store_dword v17, v27, s[76:77] offset:2976
	s_mov_b64 s[56:57], 0

.LBB0_314:
	s_nop 10
	v_add_lshl_u32 v18, v23, v18, 1
	v_and_b32_e32 v19, 1, v211
	v_cmp_eq_u32_e32 vcc, 0, v19
	v_mov_b32_e32 v20, 0x3020706
	v_mov_b32_e32 v31, 0x5040100
	v_cndmask_b32_e32 v20, v20, v31, vcc
	v_mul_u32_u24_e32 v19, 0x10e, v19
	v_add_u32_e32 v18, v18, v19
	v_add_u32_e32 v19, 0x2200, v18
	v_add_u32_e32 v18, 0x3300, v18
	v_cvt_pk_bf16_f32 v24, -v0, -v1
	v_cvt_pk_bf16_f32 v25, -v2, -v3
	v_cvt_pk_bf16_f32 v26, -v4, -v5
	v_cvt_pk_bf16_f32 v27, -v6, -v7
	v_mov_b32_dpp v28, v24 quad_perm:[1,0,3,2] row_mask:0xf bank_mask:0xf
	v_mov_b32_dpp v29, v25 quad_perm:[1,0,3,2] row_mask:0xf bank_mask:0xf
	v_mov_b32_dpp v30, v26 quad_perm:[1,0,3,2] row_mask:0xf bank_mask:0xf
	v_mov_b32_dpp v31, v27 quad_perm:[1,0,3,2] row_mask:0xf bank_mask:0xf
	v_perm_b32 v24, v28, v24, v20
	v_perm_b32 v25, v29, v25, v20
	v_perm_b32 v26, v30, v26, v20
	v_perm_b32 v27, v31, v27, v20
	global_store_dword v19, v24, s[76:77]
	global_store_dword v19, v25, s[76:77] offset:544
	global_store_dword v19, v26, s[76:77] offset:2176
	global_store_dword v19, v27, s[76:77] offset:2720
	v_cvt_pk_bf16_f32 v24, -v8, -v9
	v_cvt_pk_bf16_f32 v25, -v10, -v11
	v_cvt_pk_bf16_f32 v26, -v12, -v13
	v_cvt_pk_bf16_f32 v27, -v14, -v15
	v_mov_b32_dpp v28, v24 quad_perm:[1,0,3,2] row_mask:0xf bank_mask:0xf
	v_mov_b32_dpp v29, v25 quad_perm:[1,0,3,2] row_mask:0xf bank_mask:0xf
	v_mov_b32_dpp v30, v26 quad_perm:[1,0,3,2] row_mask:0xf bank_mask:0xf
	v_mov_b32_dpp v31, v27 quad_perm:[1,0,3,2] row_mask:0xf bank_mask:0xf
	v_perm_b32 v24, v28, v24, v20
	v_perm_b32 v25, v29, v25, v20
	v_perm_b32 v26, v30, v26, v20
	v_perm_b32 v27, v31, v27, v20
	global_store_dword v18, v24, s[76:77]
	global_store_dword v18, v25, s[76:77] offset:544
	global_store_dword v18, v26, s[76:77] offset:2176
	global_store_dword v18, v27, s[76:77] offset:2720
	s_cbranch_execnz .LBB0_301
